# static s_setprio 1 for waves 4-7 across the attention phases (strategy 4)
# baseline (speedup 1.0000x reference)
; #define LAS __attribute__((address_space(3)))
; __device__ __forceinline__ int otid(int wv) { int l; asm volatile("v_mbcnt_lo_u32_b32 %0, -1, 0\n\tv_mbcnt_hi_u32_b32 %0, -1, %0" : "=v"(l)); return wv * 64 + l; }
; __device__ __forceinline__ void attnA_phase(const Params& p, LAS unsigned char* lds, int wv) {
;     const int tid = otid(wv), lane = tid & 63, wid = __builtin_amdgcn_readfirstlane(tid >> 6), r32 = lane & 31, hi = lane >> 5;
;     const int c = wid >> 2, qg = wid & 3;
;     float lam; { float a = p.lam[lane] * p.lam[64 + lane], b2 = p.lam[128 + lane] * p.lam[192 + lane]; a = wave_sum(a); b2 = wave_sum(b2); lam = expf(a) - expf(b2) + 0.2f; }
;     const float Mq = wave_max(fabsf(p.qna[lane])), Mk = wave_max(fabsf(p.kna[lane]));
;     const unsigned char* AQ = p.ws + WS_AQ; const unsigned char* AK = p.ws + WS_AK; const unsigned char* AV = p.ws + WS_AV;
;     bf16_t* CAT = (bf16_t*)(p.ws + WS_CAT);
;     LAS float* T = (LAS float*)(lds + A_TOFF);
;     LAS float* linv = (LAS float*)(lds + A_LOFF) + wid * 32;
;     const int vblkA = (gridDim.x == 256) ? (int)((blockIdx.x & 7) * 32 + (blockIdx.x >> 3)) : (int)blockIdx.x;
;     for (int ui = vblkA; ui < 2048 * REPA; ui += gridDim.x) {
;         const int v = ui & 255, rnd = (ui >> 8) & 7, bh = v >> 2, pp = (v & 3) + 4 * (rnd >> 1), qb = (rnd & 1) ? 31 - pp : pp;
.LBB0_359:
	s_or_b64 exec, exec, s[0:1]
	v_readlane_b32 s4, v247, 1
	v_readlane_b32 s5, v247, 2
	s_waitcnt lgkmcnt(0)
	s_barrier
	s_cmp_lt_u32 s84, 0x100
	s_cbranch_scc1 .Lprio_a_skip
	s_setprio 1
.Lprio_a_skip:
	s_load_dwordx4 s[12:15], s[4:5], 0x50
	v_mbcnt_lo_u32_b32 v3, -1, 0
	v_mbcnt_hi_u32_b32 v3, -1, v3
	v_mbcnt_hi_u32_b32 v158, -1, v155
	v_and_b32_e32 v2, 63, v3
	v_lshlrev_b32_e32 v0, 2, v2
	s_waitcnt lgkmcnt(0)
	global_load_dword v1, v0, s[12:13]
	global_load_dword v4, v0, s[12:13] offset:256
	global_load_dword v5, v0, s[12:13] offset:512
	global_load_dword v6, v0, s[12:13] offset:768
	v_and_b32_e32 v220, 64, v158
	v_xor_b32_e32 v7, 1, v158
	v_add_u32_e32 v13, 64, v220
	v_cmp_lt_i32_e32 vcc, v7, v13
	v_xor_b32_e32 v8, 2, v158
	v_xor_b32_e32 v9, 4, v158
	v_cndmask_b32_e32 v7, v158, v7, vcc
	v_lshlrev_b32_e32 v214, 2, v7
	v_cmp_lt_i32_e32 vcc, v8, v13
	v_xor_b32_e32 v10, 8, v158
	v_xor_b32_e32 v11, 16, v158
	v_cndmask_b32_e32 v8, v158, v8, vcc
	v_lshlrev_b32_e32 v215, 2, v8
	v_cmp_lt_i32_e32 vcc, v9, v13
	v_xor_b32_e32 v12, 32, v158
	s_lshl_b32 s0, s80, 5
	s_lshr_b32 s2, s80, 3
	s_and_b32 s3, s0, 0xe0
	s_add_i32 s3, s3, s2
	s_cmpk_eq_i32 s82, 0x100
	v_add_u32_e32 v0, s84, v3
	s_cselect_b32 s44, s3, s80
	s_mov_b32 s1, 0
	v_readfirstlane_b32 s0, v0
	s_cmpk_gt_i32 s44, 0x7ff
	s_movk_i32 s8, 0xe0
	s_waitcnt vmcnt(2)
	v_mul_f32_e32 v7, v1, v4
	ds_bpermute_b32 v7, v214, v7
	s_waitcnt vmcnt(0)
	v_mul_f32_e32 v14, v5, v6
	ds_bpermute_b32 v14, v214, v14
	s_waitcnt lgkmcnt(1)
	v_fmac_f32_e32 v7, v1, v4
	ds_bpermute_b32 v1, v215, v7
	s_waitcnt lgkmcnt(1)
	v_fmac_f32_e32 v14, v5, v6
	ds_bpermute_b32 v4, v215, v14
	v_cndmask_b32_e32 v5, v158, v9, vcc
	v_lshlrev_b32_e32 v216, 2, v5
	s_waitcnt lgkmcnt(1)
	v_add_f32_e32 v1, v7, v1
	ds_bpermute_b32 v5, v216, v1
	s_waitcnt lgkmcnt(1)
	v_add_f32_e32 v4, v14, v4
	ds_bpermute_b32 v6, v216, v4
	v_cmp_lt_i32_e32 vcc, v10, v13
	s_waitcnt lgkmcnt(1)
	v_add_f32_e32 v1, v1, v5
	v_cndmask_b32_e32 v7, v158, v10, vcc
	v_lshlrev_b32_e32 v217, 2, v7
	s_waitcnt lgkmcnt(0)
	v_add_f32_e32 v4, v4, v6
	ds_bpermute_b32 v5, v217, v1
	ds_bpermute_b32 v6, v217, v4
	v_cmp_lt_i32_e32 vcc, v11, v13
	s_waitcnt lgkmcnt(1)
	v_add_f32_e32 v1, v1, v5
	v_cndmask_b32_e32 v7, v158, v11, vcc
	v_lshlrev_b32_e32 v218, 2, v7
	s_waitcnt lgkmcnt(0)
	v_add_f32_e32 v4, v4, v6
	ds_bpermute_b32 v5, v218, v1
	ds_bpermute_b32 v6, v218, v4
	v_cmp_lt_i32_e32 vcc, v12, v13
	s_waitcnt lgkmcnt(1)
	v_add_f32_e32 v5, v1, v5
	v_cndmask_b32_e32 v7, v158, v12, vcc
	v_lshlrev_b32_e32 v219, 2, v7
	s_waitcnt lgkmcnt(0)
	v_add_f32_e32 v1, v4, v6
	ds_bpermute_b32 v6, v219, v5
	ds_bpermute_b32 v4, v219, v1
	s_cbranch_scc1 .LBB0_394
; #define LAS __attribute__((address_space(3)))
; __device__ __forceinline__ void attnA_phase(const Params& p, LAS unsigned char* lds, int wv) {
;     ...
;     float lam; { float a = p.lam[lane] * p.lam[64 + lane], b2 = p.lam[128 + lane] * p.lam[192 + lane]; a = wave_sum(a); b2 = wave_sum(b2); lam = expf(a) - expf(b2) + 0.2f; }
;     const float Mq = wave_max(fabsf(p.qna[lane])), Mk = wave_max(fabsf(p.kna[lane]));
;     const unsigned char* AQ = p.ws + WS_AQ; const unsigned char* AK = p.ws + WS_AK; const unsigned char* AV = p.ws + WS_AV;
;     bf16_t* CAT = (bf16_t*)(p.ws + WS_CAT);
;     LAS float* T = (LAS float*)(lds + A_TOFF);
;     LAS float* linv = (LAS float*)(lds + A_LOFF) + wid * 32;
;     const int vblkA = (gridDim.x == 256) ? (int)((blockIdx.x & 7) * 32 + (blockIdx.x >> 3)) : (int)blockIdx.x;
;     for (int ui = vblkA; ui < 2048 * REPA; ui += gridDim.x) {
;         const int v = ui & 255, rnd = (ui >> 8) & 7, bh = v >> 2, pp = (v & 3) + 4 * (rnd >> 1), qb = (rnd & 1) ? 31 - pp : pp;
;         const int b = bh >> 2, h = bh & 3, q0 = qb * 128, NT = 2 * qb + 2;
;         const size_t tokbase = (size_t)b * SEQ;
;         if (tid < 320) { const int d = 223 - tid;
;             T[tid] = d < 0 ? -1e30f : (p.rel_bias[t5_bucket(min(d, 127)) * 12 + h] - p.rel_bias[31 * 12 + h]) * LOG2E; }
;         bf16x8 qf[4];
;         { const unsigned char* Qp = AQ + (tokbase + q0 + 32 * qg + r32) * 1024 + h * 256 + c * 128 + hi * 16;
; #pragma unroll
;           for (int ds = 0; ds < 4; ++ds) qf[ds] = *(const bf16x8*)(Qp + 32 * ds); }
;         const int qpos = q0 + 32 * qg + r32, qw0 = q0 + 32 * qg;
;         f32x16 O[4];
; #pragma unroll
;         for (int e = 0; e < 4; ++e)
; #pragma unroll
;             for (int r = 0; r < 16; ++r) O[e][r] = 0.f;
;         float l = 0.f;
;         u32x4 kreg[2], vreg[2];
;         const int srow = tid >> 4, sch = tid & 15;
	s_waitcnt lgkmcnt(1)
	v_add_f32_e32 v5, v5, v6
	s_load_dwordx2 s[24:25], s[4:5], 0xa0
	s_load_dwordx2 s[2:3], s[4:5], 0x90
	s_mov_b32 s7, 0x3fb8aa3b
	v_mul_f32_e32 v6, 0x3fb8aa3b, v5
	v_fma_f32 v7, v5, s7, -v6
	v_rndne_f32_e32 v8, v6
	v_fmac_f32_e32 v7, 0x32a5705f, v5
	v_sub_f32_e32 v6, v6, v8
	v_add_f32_e32 v6, v6, v7
	s_waitcnt lgkmcnt(0)
	s_add_u32 s4, s24, 0x9a00000
	v_exp_f32_e32 v6, v6
	v_cvt_i32_f32_e32 v7, v8
	s_addc_u32 s5, s25, 0
	s_add_u32 s16, s24, 0xda00000
	v_add_f32_e32 v1, v1, v4
	s_addc_u32 s17, s25, 0
	v_mul_f32_e32 v4, 0x3fb8aa3b, v1
	s_add_u32 s18, s24, 0x11a00000
	v_ldexp_f32 v6, v6, v7
	v_fma_f32 v7, v1, s7, -v4
	v_rndne_f32_e32 v8, v4
	s_addc_u32 s19, s25, 0
	s_ashr_i32 s6, s0, 6
	v_fmac_f32_e32 v7, 0x32a5705f, v1
	v_sub_f32_e32 v4, v4, v8
	s_lshl_b32 s9, s6, 7
	v_add_f32_e32 v4, v4, v7
	s_add_i32 s9, s9, 0
	v_exp_f32_e32 v4, v4
	v_cvt_i32_f32_e32 v7, v8
	s_add_i32 s28, s9, 0x12d00
	s_mov_b32 s9, 0xc2ce8ed0
	v_cmp_ngt_f32_e32 vcc, s9, v5
	s_mov_b32 s10, 0x42b17218
	v_mov_b32_e32 v8, 0x7f800000
	v_cndmask_b32_e32 v6, 0, v6, vcc
	v_cmp_nlt_f32_e32 vcc, s10, v5
	v_ldexp_f32 v4, v4, v7
	s_movk_i32 s29, 0x140
	v_cndmask_b32_e32 v5, v8, v6, vcc
	v_cmp_ngt_f32_e32 vcc, s9, v1
	v_sub_u32_e32 v6, 0xdf, v0
	v_and_b32_e32 v159, 31, v3
	v_cndmask_b32_e32 v4, 0, v4, vcc
	v_cmp_nlt_f32_e32 vcc, s10, v1
	s_movk_i32 s10, 0x42
	s_and_b32 s22, s6, 3
	v_cndmask_b32_e32 v1, v8, v4, vcc
	v_sub_f32_e32 v1, v5, v1
	v_cmp_lt_u32_e32 vcc, 18, v6
	v_add_f32_e32 v4, 0x3e4ccccd, v1
	s_ashr_i32 s12, s0, 8
	v_cndmask_b32_e64 v1, 16, 17, vcc
	v_cmp_lt_u32_e32 vcc, 20, v6
	v_cmp_gt_i32_e64 s[6:7], s29, v0
	v_cmp_gt_i32_e64 s[8:9], s8, v0
	v_cndmask_b32_e64 v8, 0, 1, vcc
	v_cmp_lt_u32_e32 vcc, 23, v6
	v_ashrrev_i32_e32 v148, 4, v0
	s_lshl_b32 s20, s12, 7
	v_addc_co_u32_e32 v1, vcc, v1, v8, vcc
	v_cmp_lt_u32_e32 vcc, 26, v6
	v_lshrrev_b32_e32 v10, 1, v3
	s_lshl_b32 s34, s22, 5
	v_cndmask_b32_e64 v8, 0, 1, vcc
	v_cmp_lt_u32_e32 vcc, 30, v6
	s_ashr_i32 s21, s20, 31
	v_and_b32_e32 v10, 4, v10
	v_addc_co_u32_e32 v1, vcc, v1, v8, vcc
	v_cmp_lt_u32_e32 vcc, 34, v6
	v_and_b32_e32 v11, 19, v3
	v_lshrrev_b32_e32 v5, 5, v2
	v_cndmask_b32_e64 v8, 0, 1, vcc
	v_cmp_lt_u32_e32 vcc, 39, v6
	v_min_u32_e32 v7, 0x7f, v6
	v_ashrrev_i32_e32 v149, 31, v148
	v_addc_co_u32_e32 v1, vcc, v1, v8, vcc
	v_cmp_lt_u32_e32 vcc, 45, v6
	v_lshlrev_b32_e32 v164, 3, v5
	v_lshlrev_b32_e32 v171, 2, v5
	v_cndmask_b32_e64 v8, 0, 1, vcc
	v_cmp_lt_u32_e32 vcc, 51, v6
	v_lshlrev_b32_e32 v146, 4, v5
	s_mov_b64 s[26:27], 0x20400000
	v_addc_co_u32_e32 v1, vcc, v1, v8, vcc
	v_cmp_lt_u32_e32 vcc, 58, v6
	v_or_b32_e32 v176, 1, v171
	v_or_b32_e32 v177, 2, v171
	v_cndmask_b32_e64 v8, 0, 1, vcc
	v_cmp_lt_u32_e32 vcc, s10, v6
	s_movk_i32 s10, 0x4c
	v_or_b32_e32 v178, 3, v171
	v_addc_co_u32_e32 v1, vcc, v1, v8, vcc
	v_cmp_lt_u32_e32 vcc, s10, v6
	s_movk_i32 s10, 0x56
	v_or_b32_e32 v179, 8, v171
	v_cndmask_b32_e64 v8, 0, 1, vcc
	v_cmp_lt_u32_e32 vcc, s10, v6
	s_movk_i32 s10, 0x62
	v_or_b32_e32 v180, 9, v171
	v_addc_co_u32_e32 v1, vcc, v1, v8, vcc
	v_cmp_lt_u32_e32 vcc, s10, v6
	s_movk_i32 s10, 0x70
	v_or_b32_e32 v181, 10, v171
	v_cndmask_b32_e64 v8, 0, 1, vcc
	v_cmp_lt_u32_e32 vcc, s10, v6
	s_add_i32 s10, 0, 0x12800
	v_lshl_add_u32 v160, v0, 2, s10
	v_lshlrev_b32_e32 v0, 4, v3
	v_and_b32_e32 v161, 0xf0, v0
	v_lshlrev_b32_e32 v0, 1, v159
	v_and_b32_e32 v9, 8, v0
	v_or3_b32 v9, v10, v11, v9
	s_cmp_eq_u32 s12, 1
	v_mul_u32_u24_e32 v163, 0x110, v9
	v_lshrrev_b32_e32 v9, 2, v3
	v_and_b32_e32 v10, 16, v3
	v_lshlrev_b32_e32 v3, 2, v3
	s_cselect_b64 s[12:13], -1, 0
	s_lshl_b32 s22, s22, 14
	v_and_or_b32 v3, v3, 12, v10
	v_cmp_gt_u32_e64 s[10:11], 32, v2
	v_lshlrev_b32_e32 v2, 2, v159
	s_add_i32 s22, s22, 0
	v_addc_co_u32_e32 v8, vcc, v1, v8, vcc
	v_mov_b32_e32 v1, 0
	v_lshlrev_b32_e32 v166, 1, v3
	v_lshlrev_b32_e32 v3, 11, v5
	v_add_u32_e32 v10, s22, v2
	v_add_u32_e32 v170, v10, v3
	v_cmp_gt_u32_e32 vcc, 16, v6
	v_mov_b32_e32 v3, v1
	v_and_or_b32 v9, v9, 3, v164
	v_cndmask_b32_e64 v168, 1.0, v4, s[12:13]
	v_add_u32_e32 v169, s28, v2
	v_lshl_add_u64 v[4:5], s[24:25], 0, v[0:1]
	v_cndmask_b32_e32 v0, v8, v7, vcc
	v_or_b32_e32 v182, 11, v171
	v_or_b32_e32 v183, 16, v171
	v_or_b32_e32 v184, 17, v171
	v_or_b32_e32 v185, 18, v171
	v_or_b32_e32 v186, 19, v171
	v_or_b32_e32 v187, 24, v171
	v_or_b32_e32 v188, 25, v171
	v_or_b32_e32 v189, 26, v171
	v_or_b32_e32 v190, 27, v171
	v_lshl_add_u64 v[152:153], s[14:15], 0, v[2:3]
	v_lshlrev_b64 v[2:3], 10, v[148:149]
	s_movk_i32 s30, 0x110
	s_cmpk_lt_u32 s0, 0x100
	v_lshl_add_u64 v[150:151], v[4:5], 0, s[26:27]
	v_mul_lo_u32 v172, v0, 12
	v_mul_u32_u24_e32 v175, 0x140, v9
	v_lshlrev_b32_e32 v0, 9, v176
	v_lshlrev_b32_e32 v4, 9, v177
	v_lshlrev_b32_e32 v5, 9, v178
	v_lshlrev_b32_e32 v6, 9, v179
	v_lshlrev_b32_e32 v7, 9, v180
	v_lshlrev_b32_e32 v8, 9, v181
	v_lshlrev_b32_e32 v9, 9, v182
	v_lshlrev_b32_e32 v11, 9, v183
	v_lshlrev_b32_e32 v12, 9, v184
	v_lshlrev_b32_e32 v13, 9, v185
	v_lshlrev_b32_e32 v14, 9, v186
	v_lshlrev_b32_e32 v15, 9, v187
	v_lshlrev_b32_e32 v16, 9, v188
	v_lshlrev_b32_e32 v17, 9, v189
	v_lshlrev_b32_e32 v18, 9, v190
	v_lshl_add_u64 v[2:3], s[24:25], 0, v[2:3]
	s_mov_b64 s[14:15], 0x11a18000
	v_mov_b32_e32 v147, v1
	v_add_u32_e32 v162, 0, v161
	v_add_u32_e32 v165, 0xdf, v164
	v_add_u32_e32 v167, 0xff, v164
	s_cselect_b64 s[22:23], -1, 0
	v_mul_lo_u32 v173, v148, s30
	v_mul_lo_u32 v174, v148, s29
	v_or_b32_e32 v191, s34, v159
	v_lshl_add_u64 v[154:155], v[2:3], 0, s[14:15]
	s_lshl_b32 s35, s44, 8
	s_lshl_b32 s36, s82, 8
	s_mov_b64 s[24:25], 0x8000
	s_mov_b64 s[26:27], 0x10000
	v_add_u32_e32 v192, s28, v146
	v_mov_b32_e32 v193, 0x358637bd
	s_mov_b32 s37, 0xf800000
	v_mov_b32_e32 v194, 0x260
	v_add_u32_e32 v195, v10, v0
	v_add_u32_e32 v196, v10, v4
	v_add_u32_e32 v197, v10, v5
	v_add_u32_e32 v198, v10, v6
	v_add_u32_e32 v199, v10, v7
	v_add_u32_e32 v200, v10, v8
	v_add_u32_e32 v201, v10, v9
	v_add_u32_e32 v202, v10, v11
	v_add_u32_e32 v203, v10, v12
	v_add_u32_e32 v204, v10, v13
	v_add_u32_e32 v205, v10, v14
	v_add_u32_e32 v206, v10, v15
	v_add_u32_e32 v207, v10, v16
	v_add_u32_e32 v208, v10, v17
	v_add_u32_e32 v209, v10, v18
	s_mov_b32 s38, s44
	s_branch .LBB0_362

; __device__ __forceinline__ unsigned xb_add(unsigned* p, unsigned v) { return __hip_atomic_fetch_add(p, v, __ATOMIC_RELAXED, __HIP_MEMORY_SCOPE_AGENT); }
; __device__ __forceinline__ void xcd_barrier(const XcdBarrier& b) {
;     asm volatile("s_waitcnt vmcnt(0)" ::: "memory");
;     __syncthreads();
;     if (threadIdx.x == 0) {
;         unsigned* bar = b.bar;
;         __builtin_amdgcn_s_waitcnt(0);
;         unsigned nloc = b.st[0], nx = b.st[1];
;         if (nloc == 0u) { xcd_barrier_complete(bar, b.x, nloc, nx); b.st[0] = nloc; b.st[1] = nx; }
;         const unsigned old = xb_add(&bar[XB_XSUB(b.x)], 1u);
.LBB0_752:
	s_setprio 0
	s_waitcnt vmcnt(0)
	s_barrier
	s_mov_b64 s[0:1], exec
	v_readlane_b32 s2, v247, 8
	v_readlane_b32 s3, v247, 9
	s_and_b64 s[2:3], s[0:1], s[2:3]
	s_mov_b64 exec, s[2:3]
	s_cbranch_execz .LBB0_804
	s_add_i32 s2, 0, 0x23ff0
	v_mov_b32_e32 v0, s2
	s_waitcnt vmcnt(0) expcnt(0) lgkmcnt(0)
	ds_read_b32 v2, v0
	s_add_i32 s2, 0, 0x23ff4
	v_mov_b32_e32 v0, s2
	ds_read_b32 v0, v0
	s_waitcnt lgkmcnt(1)
	v_cmp_ne_u32_e32 vcc, 0, v2
	s_cbranch_vccnz .LBB0_768
	v_readlane_b32 s2, v247, 0
	v_readlane_b32 s36, v247, 3
	s_mul_i32 s33, s83, s2
	v_readlane_b32 s37, v247, 4
	s_add_u32 s2, s36, 0xc0200
	s_addc_u32 s3, s37, 0
	s_add_u32 s4, s36, 0xc0400
	s_addc_u32 s5, s37, 0
	s_add_u32 s6, s36, 0xc0500
	s_addc_u32 s7, s37, 0
	s_add_u32 s8, s36, 0xc0600
	s_addc_u32 s9, s37, 0
	s_add_u32 s10, s36, 0xc0700
	s_addc_u32 s11, s37, 0
	s_add_u32 s12, s36, 0xc0800
	s_addc_u32 s13, s37, 0
	s_add_u32 s14, s36, 0xc0900
	s_addc_u32 s15, s37, 0
	s_add_u32 s16, s36, 0xc0a00
	s_addc_u32 s17, s37, 0
	s_add_u32 s18, s36, 0xc0b00
	s_addc_u32 s19, s37, 0
	s_add_u32 s20, s36, 0xc0c00
	s_addc_u32 s21, s37, 0
	s_add_u32 s22, s36, 0xc0d00
	s_addc_u32 s23, s37, 0
	s_add_u32 s24, s36, 0xc0e00
	s_addc_u32 s25, s37, 0
	s_add_u32 s26, s36, 0xc0f00
	s_addc_u32 s27, s37, 0
	s_add_u32 s28, s36, 0xc1000
	s_addc_u32 s29, s37, 0
	s_add_u32 s30, s36, 0xc1100
	s_addc_u32 s31, s37, 0
	s_add_u32 s34, s36, 0xc1200
	s_addc_u32 s35, s37, 0
	s_add_u32 s36, s36, 0xc1300
	s_mul_i32 s33, s33, s82
	s_addc_u32 s37, s37, 0
	s_mov_b32 s44, 1
	v_mov_b32_e32 v16, 0
	s_branch .LBB0_756
